# stack25 with the PARK job on workgroup 0 (a GEMM workgroup, before its seam-2 arrival) instead of the last conv-only workgroup
# speedup vs baseline: 1.0044x; 1.0006x over previous
.LBB0_504:
	s_mov_b32 s0, 0
	s_cmp_lg_u32 s78, s0
	s_cbranch_scc1 .Lsp2_nopark
	s_waitcnt vmcnt(0)
	v_lshlrev_b32_e32 v2, 7, v0
	v_and_b32_e32 v2, 0x8000, v2
	v_mov_b32_e32 v3, 0
	v_lshl_add_u64 v[4:5], s[76:77], 0, v[2:3]
	v_mov_b32_e32 v2, 2
	v_lshlrev_b32_sdwa v2, v2, v0 dst_sel:DWORD dst_unused:UNUSED_PAD src0_sel:DWORD src1_sel:BYTE_0
	v_lshl_add_u64 v[4:5], v[4:5], 0, v[2:3]
	s_mov_b64 s[0:1], 0x8923400
	v_lshl_add_u64 v[6:7], v[4:5], 0, s[0:1]
	s_mov_b32 s0, 0x8923000
	v_add_co_u32_e32 v8, vcc, s0, v4
	s_mov_b32 s0, 0x8924000
	s_nop 0
	v_addc_co_u32_e32 v9, vcc, 0, v5, vcc
	v_add_co_u32_e32 v10, vcc, s0, v4
	s_mov_b32 s0, 0x8925000
	s_nop 0
	v_addc_co_u32_e32 v11, vcc, 0, v5, vcc
	v_add_co_u32_e32 v12, vcc, s0, v4
	s_mov_b32 s0, 0x8926000
	s_nop 0
	v_addc_co_u32_e32 v13, vcc, 0, v5, vcc
	global_load_dword v14, v[8:9], off offset:1024
	global_load_dword v15, v[6:7], off offset:1024
	global_load_dword v16, v[6:7], off offset:2048
	global_load_dword v17, v[10:11], off offset:1024
	global_load_dword v18, v[10:11], off offset:2048
	global_load_dword v19, v[10:11], off offset:3072
	global_load_dword v20, v[12:13], off offset:1024
	global_load_dword v21, v[6:7], off offset:3072
	v_add_co_u32_e32 v6, vcc, s0, v4
	s_mov_b32 s0, 0x8927000
	s_nop 0
	v_addc_co_u32_e32 v7, vcc, 0, v5, vcc
	global_load_dword v22, v[12:13], off offset:2048
	global_load_dword v23, v[12:13], off offset:3072
	v_add_co_u32_e32 v8, vcc, s0, v4
	s_mov_b32 s0, 0x8928000
	s_nop 0
	v_addc_co_u32_e32 v9, vcc, 0, v5, vcc
	v_add_co_u32_e32 v10, vcc, s0, v4
	s_mov_b32 s0, 0x8929000
	s_nop 0
	v_addc_co_u32_e32 v11, vcc, 0, v5, vcc
	global_load_dword v24, v[6:7], off offset:-4096
	global_load_dword v25, v[6:7], off
	global_load_dword v26, v[6:7], off offset:1024
	global_load_dword v27, v[6:7], off offset:2048
	global_load_dword v28, v[6:7], off offset:3072
	global_load_dword v29, v[10:11], off offset:-4096
	global_load_dword v30, v[10:11], off
	v_add_co_u32_e32 v6, vcc, s0, v4
	s_mov_b32 s0, 0x892a000
	s_nop 0
	v_addc_co_u32_e32 v7, vcc, 0, v5, vcc
	v_add_co_u32_e32 v12, vcc, s0, v4
	v_lshlrev_b32_e32 v2, 2, v0
	s_nop 0
	v_addc_co_u32_e32 v13, vcc, 0, v5, vcc
	global_load_dword v31, v[8:9], off offset:1024
	global_load_dword v32, v[8:9], off offset:2048
	global_load_dword v33, v[8:9], off offset:3072
	global_load_dword v34, v[6:7], off offset:1024
	global_load_dword v35, v[6:7], off offset:2048
	global_load_dword v36, v[6:7], off offset:3072
	global_load_dword v37, v[10:11], off offset:1024
	global_load_dword v38, v[10:11], off offset:2048
	global_load_dword v39, v[10:11], off offset:3072
	global_load_dword v40, v[12:13], off offset:-4096
	global_load_dword v41, v[12:13], off
	global_load_dword v42, v[12:13], off offset:1024
	global_load_dword v43, v[12:13], off offset:2048
	global_load_dword v44, v[12:13], off offset:3072
	v_add_co_u32_e32 v4, vcc, 0x892b000, v4
	v_lshl_add_u64 v[2:3], s[76:77], 0, v[2:3]
	s_nop 0
	v_addc_co_u32_e32 v5, vcc, 0, v5, vcc
	global_load_dword v4, v[4:5], off
	v_add_co_u32_e32 v2, vcc, 0x1ce33000, v2
	s_waitcnt vmcnt(31)
	v_add_f32_e32 v5, 0, v14
	s_waitcnt vmcnt(30)
	v_add_f32_e32 v5, v5, v15
	s_waitcnt vmcnt(29)
	v_add_f32_e32 v5, v5, v16
	v_addc_co_u32_e32 v3, vcc, 0, v3, vcc
	s_waitcnt vmcnt(24)
	v_add_f32_e32 v5, v5, v21
	v_add_f32_e32 v5, v5, v17
	v_add_f32_e32 v5, v5, v18
	v_add_f32_e32 v5, v5, v19
	s_waitcnt vmcnt(21)
	v_add_f32_e32 v5, v5, v24
	v_add_f32_e32 v5, v5, v20
	v_add_f32_e32 v5, v5, v22
	v_add_f32_e32 v5, v5, v23
	s_waitcnt vmcnt(20)
	v_add_f32_e32 v5, v5, v25
	s_waitcnt vmcnt(19)
	v_add_f32_e32 v5, v5, v26
	s_waitcnt vmcnt(18)
	v_add_f32_e32 v5, v5, v27
	s_waitcnt vmcnt(17)
	v_add_f32_e32 v5, v5, v28
	s_waitcnt vmcnt(16)
	v_add_f32_e32 v5, v5, v29
	s_waitcnt vmcnt(14)
	v_add_f32_e32 v5, v5, v31
	s_waitcnt vmcnt(13)
	v_add_f32_e32 v5, v5, v32
	s_waitcnt vmcnt(12)
	v_add_f32_e32 v5, v5, v33
	v_add_f32_e32 v5, v5, v30
	s_waitcnt vmcnt(8)
	v_add_f32_e32 v5, v5, v37
	s_waitcnt vmcnt(7)
	v_add_f32_e32 v5, v5, v38
	s_waitcnt vmcnt(6)
	v_add_f32_e32 v5, v5, v39
	s_waitcnt vmcnt(5)
	v_add_f32_e32 v5, v5, v40
	v_add_f32_e32 v5, v5, v34
	v_add_f32_e32 v5, v5, v35
	v_add_f32_e32 v5, v5, v36
	s_waitcnt vmcnt(4)
	v_add_f32_e32 v5, v5, v41
	s_waitcnt vmcnt(3)
	v_add_f32_e32 v5, v5, v42
	s_waitcnt vmcnt(2)
	v_add_f32_e32 v5, v5, v43
	s_waitcnt vmcnt(1)
	v_add_f32_e32 v5, v5, v44
	s_waitcnt vmcnt(0)
	v_add_f32_e32 v4, v5, v4
	global_store_dword v[2:3], v4, off offset:1024
